# NSA gated cross-branch accumulator kept in 32 VGPRs instead of a global bf16 scratch buffer (removes 32 stores, 32 loads and two dependent round trips per NSA unit); on top of v36
# speedup vs baseline: 1.0082x; 1.0082x over previous
; __device__ __forceinline__ u32x2 pack4(f32x4 v) { u32x2 w; w.x = cvtpk(v[0], v[1]); w.y = cvtpk(v[2], v[3]); return w; }
; __device__ __forceinline__ unsigned pack4_fp8(float a, float b, float c, float d) { unsigned w = 0u; w = (unsigned)__builtin_amdgcn_cvt_pk_fp8_f32(a, b, (int)w, false); w = (unsigned)__builtin_amdgcn_cvt_pk_fp8_f32(c, d, (int)w, true); return w; }
; __device__ __forceinline__ void nsa_unit(Frame& F, int b, int g, int c) {
;     ...
;     { const float sc = l > 0.f ? gw / l : 0.f; unsigned char* orow = ws + WS_H + ((((trow >> 8) * 32) + hg) * 256 + (trow & 255)) * 128;
; #pragma unroll
;       for (int db = 0; db < 4; ++db)
; #pragma unroll
;           for (int q4 = 0; q4 < 4; ++q4) { const bf16_t* p = accb + 32 * db + 8 * q4 + 4 * hi; f32x4 o = {O[db][4 * q4], O[db][4 * q4 + 1], O[db][4 * q4 + 2], O[db][4 * q4 + 3]}; const u32x2 w = *(const u32x2*)p;
;               const f32x4 pr = {__uint_as_float(w.x << 16), __uint_as_float(w.x & 0xffff0000u), __uint_as_float(w.y << 16), __uint_as_float(w.y & 0xffff0000u)};
;               const f32x4 r = pr + o * sc;
;               if constexpr (FP8_OUT) *(unsigned*)(orow + 32 * db + 8 * q4 + 4 * hi) = pack4_fp8(r[0] * 16.0f, r[1] * 16.0f, r[2] * 16.0f, r[3] * 16.0f);
;               else *(u32x2*)((bf16_t*)(ws + WS_H) + trow * 4096 + hg * 128 + 32 * db + 8 * q4 + 4 * hi) = pack4(r); } }
.LBB0_839:
	v_div_scale_f32 v66, s[0:1], v67, v67, v148
	v_rcp_f32_e32 v75, v66
	v_lshlrev_b32_e32 v73, 7, v154
	v_and_b32_e32 v150, 0x7f80, v73
	v_div_scale_f32 v72, vcc, v148, v67, v148
	v_fma_f32 v73, -v66, v75, 1.0
	v_fmac_f32_e32 v75, v73, v75
	v_mul_f32_e32 v73, v72, v75
	v_fma_f32 v76, -v66, v73, v72
	v_fmac_f32_e32 v73, v76, v75
	v_fma_f32 v66, -v66, v73, v72
	v_div_fmas_f32 v66, v66, v75, v73
	v_div_fixup_f32 v66, v66, v67, v148
	v_cmp_lt_f32_e32 vcc, 0, v67
	v_mov_b32_e32 v74, v151
	v_lshrrev_b64 v[70:71], 3, v[156:157]
	v_cndmask_b32_e32 v66, 0, v66, vcc
	s_movk_i32 s0, 0xffe0
	v_and_b32_e32 v71, 0x1ffff, v71
	v_and_or_b32 v70, v70, s0, v149
	v_readlane_b32 s0, v245, 61
	v_lshlrev_b64 v[70:71], 15, v[70:71]
	v_readlane_b32 s1, v245, 62
	s_and_b64 vcc, exec, s[96:97]
	v_lshlrev_b32_e32 v72, 16, v220
	v_and_b32_e32 v73, 0xffff0000, v220
	v_pk_fma_f32 v[50:51], v[66:67], v[50:51], v[72:73] op_sel_hi:[0,1,1]
	v_mul_f32_e32 v50, 0x41800000, v50
	v_mul_f32_e32 v51, 0x41800000, v51
	v_cvt_pk_fp8_f32 v74, v50, v51
	v_lshlrev_b32_e32 v68, 16, v221
	v_and_b32_e32 v69, 0xffff0000, v221
	v_pk_fma_f32 v[50:51], v[66:67], v[52:53], v[68:69] op_sel_hi:[0,1,1]
	v_mul_f32_e32 v50, 0x41800000, v50
	v_mul_f32_e32 v51, 0x41800000, v51
	v_cvt_pk_fp8_f32 v74, v50, v51 op_sel:[0,0,1]
	v_lshl_add_u64 v[50:51], s[0:1], 0, v[70:71]
	v_lshl_add_u64 v[50:51], v[50:51], 0, v[150:151]
	v_lshl_add_u64 v[50:51], v[50:51], 0, v[158:159]
	global_store_dword v[50:51], v74, off
	v_mov_b32_e32 v67, v151
	s_mov_b64 s[0:1], 0
	v_lshlrev_b32_e32 v68, 16, v222
	v_and_b32_e32 v69, 0xffff0000, v222
	v_pk_fma_f32 v[54:55], v[66:67], v[54:55], v[68:69] op_sel_hi:[0,1,1]
	v_mul_f32_e32 v54, 0x41800000, v54
	v_mul_f32_e32 v55, 0x41800000, v55
	v_cvt_pk_fp8_f32 v67, v54, v55
	v_lshlrev_b32_e32 v52, 16, v223
	v_and_b32_e32 v53, 0xffff0000, v223
	v_pk_fma_f32 v[52:53], v[66:67], v[56:57], v[52:53] op_sel_hi:[0,1,1]
	v_mul_f32_e32 v52, 0x41800000, v52
	v_mul_f32_e32 v53, 0x41800000, v53
	v_cvt_pk_fp8_f32 v67, v52, v53 op_sel:[0,0,1]
	v_mov_b32_e32 v56, v151
	global_store_dword v[50:51], v67, off offset:8
	v_lshlrev_b32_e32 v54, 16, v224
	v_and_b32_e32 v55, 0xffff0000, v224
	v_pk_fma_f32 v[54:55], v[66:67], v[58:59], v[54:55] op_sel_hi:[0,1,1]
	v_mul_f32_e32 v54, 0x41800000, v54
	v_mul_f32_e32 v55, 0x41800000, v55
	v_cvt_pk_fp8_f32 v56, v54, v55
	v_lshlrev_b32_e32 v52, 16, v225
	v_and_b32_e32 v53, 0xffff0000, v225
	v_pk_fma_f32 v[52:53], v[66:67], v[60:61], v[52:53] op_sel_hi:[0,1,1]
	v_mul_f32_e32 v52, 0x41800000, v52
	v_mul_f32_e32 v53, 0x41800000, v53
	v_cvt_pk_fp8_f32 v56, v52, v53 op_sel:[0,0,1]
	global_store_dword v[50:51], v56, off offset:16
	v_mov_b32_e32 v56, v151
	v_lshlrev_b32_e32 v54, 16, v226
	v_and_b32_e32 v55, 0xffff0000, v226
	v_pk_fma_f32 v[54:55], v[66:67], v[62:63], v[54:55] op_sel_hi:[0,1,1]
	v_mul_f32_e32 v54, 0x41800000, v54
	v_mul_f32_e32 v55, 0x41800000, v55
	v_cvt_pk_fp8_f32 v56, v54, v55
	v_lshlrev_b32_e32 v52, 16, v227
	v_and_b32_e32 v53, 0xffff0000, v227
	v_pk_fma_f32 v[52:53], v[66:67], v[64:65], v[52:53] op_sel_hi:[0,1,1]
	v_mul_f32_e32 v52, 0x41800000, v52
	v_mul_f32_e32 v53, 0x41800000, v53
	v_cvt_pk_fp8_f32 v56, v52, v53 op_sel:[0,0,1]
	global_store_dword v[50:51], v56, off offset:24
	v_mov_b32_e32 v56, v151
	v_lshlrev_b32_e32 v54, 16, v228
	v_and_b32_e32 v55, 0xffff0000, v228
	v_pk_fma_f32 v[34:35], v[66:67], v[34:35], v[54:55] op_sel_hi:[0,1,1]
	v_mul_f32_e32 v34, 0x41800000, v34
	v_mul_f32_e32 v35, 0x41800000, v35
	v_cvt_pk_fp8_f32 v56, v34, v35
	v_lshlrev_b32_e32 v52, 16, v229
	v_and_b32_e32 v53, 0xffff0000, v229
	v_pk_fma_f32 v[34:35], v[66:67], v[36:37], v[52:53] op_sel_hi:[0,1,1]
	v_mul_f32_e32 v34, 0x41800000, v34
	v_mul_f32_e32 v35, 0x41800000, v35
	v_cvt_pk_fp8_f32 v56, v34, v35 op_sel:[0,0,1]
	v_mov_b32_e32 v52, v151
	global_store_dword v[50:51], v56, off offset:32
	v_lshlrev_b32_e32 v36, 16, v230
	v_and_b32_e32 v37, 0xffff0000, v230
	v_pk_fma_f32 v[36:37], v[66:67], v[38:39], v[36:37] op_sel_hi:[0,1,1]
	v_mul_f32_e32 v36, 0x41800000, v36
	v_mul_f32_e32 v37, 0x41800000, v37
	v_cvt_pk_fp8_f32 v52, v36, v37
	v_lshlrev_b32_e32 v34, 16, v231
	v_and_b32_e32 v35, 0xffff0000, v231
	v_pk_fma_f32 v[34:35], v[66:67], v[40:41], v[34:35] op_sel_hi:[0,1,1]
	v_mul_f32_e32 v34, 0x41800000, v34
	v_mul_f32_e32 v35, 0x41800000, v35
	v_cvt_pk_fp8_f32 v52, v34, v35 op_sel:[0,0,1]
	v_mov_b32_e32 v38, v151
	global_store_dword v[50:51], v52, off offset:40
	v_lshlrev_b32_e32 v36, 16, v232
	v_and_b32_e32 v37, 0xffff0000, v232
	v_pk_fma_f32 v[36:37], v[66:67], v[42:43], v[36:37] op_sel_hi:[0,1,1]
	v_mul_f32_e32 v36, 0x41800000, v36
	v_mul_f32_e32 v37, 0x41800000, v37
	v_cvt_pk_fp8_f32 v38, v36, v37
	v_lshlrev_b32_e32 v34, 16, v233
	v_and_b32_e32 v35, 0xffff0000, v233
	v_pk_fma_f32 v[34:35], v[66:67], v[44:45], v[34:35] op_sel_hi:[0,1,1]
	v_mul_f32_e32 v34, 0x41800000, v34
	v_mul_f32_e32 v35, 0x41800000, v35
	v_cvt_pk_fp8_f32 v38, v34, v35 op_sel:[0,0,1]
	global_store_dword v[50:51], v38, off offset:48
	v_mov_b32_e32 v38, v151
	v_lshlrev_b32_e32 v36, 16, v234
	v_and_b32_e32 v37, 0xffff0000, v234
; __device__ __forceinline__ u32x2 pack4(f32x4 v) { u32x2 w; w.x = cvtpk(v[0], v[1]); w.y = cvtpk(v[2], v[3]); return w; }
; __device__ __forceinline__ unsigned pack4_fp8(float a, float b, float c, float d) { unsigned w = 0u; w = (unsigned)__builtin_amdgcn_cvt_pk_fp8_f32(a, b, (int)w, false); w = (unsigned)__builtin_amdgcn_cvt_pk_fp8_f32(c, d, (int)w, true); return w; }
; __device__ __forceinline__ void nsa_unit(Frame& F, int b, int g, int c) {
;     ...
;     { const float sc = l > 0.f ? gw / l : 0.f; unsigned char* orow = ws + WS_H + ((((trow >> 8) * 32) + hg) * 256 + (trow & 255)) * 128;
; #pragma unroll
;       for (int db = 0; db < 4; ++db)
; #pragma unroll
;           for (int q4 = 0; q4 < 4; ++q4) { const bf16_t* p = accb + 32 * db + 8 * q4 + 4 * hi; f32x4 o = {O[db][4 * q4], O[db][4 * q4 + 1], O[db][4 * q4 + 2], O[db][4 * q4 + 3]}; const u32x2 w = *(const u32x2*)p;
;               const f32x4 pr = {__uint_as_float(w.x << 16), __uint_as_float(w.x & 0xffff0000u), __uint_as_float(w.y << 16), __uint_as_float(w.y & 0xffff0000u)};
;               const f32x4 r = pr + o * sc;
;               if constexpr (FP8_OUT) *(unsigned*)(orow + 32 * db + 8 * q4 + 4 * hi) = pack4_fp8(r[0] * 16.0f, r[1] * 16.0f, r[2] * 16.0f, r[3] * 16.0f);
;               else *(u32x2*)((bf16_t*)(ws + WS_H) + trow * 4096 + hg * 128 + 32 * db + 8 * q4 + 4 * hi) = pack4(r); } }
; __global__ void __launch_bounds__(512, 2) fwd(Args args) {
;     ...
;         for (int item = F.vcu; item < 512; item += F.G) { const int bg = item >> 5, p = item & 31;
;             for (int h2 = 0; h2 < 2; ++h2) att::nsa_unit(F, bg >> 2, bg & 3, h2 ? p : 63 - p); }
	v_pk_fma_f32 v[36:37], v[66:67], v[46:47], v[36:37] op_sel_hi:[0,1,1]
	v_mul_f32_e32 v36, 0x41800000, v36
	v_mul_f32_e32 v37, 0x41800000, v37
	v_cvt_pk_fp8_f32 v38, v36, v37
	v_lshlrev_b32_e32 v34, 16, v235
	v_and_b32_e32 v35, 0xffff0000, v235
	v_pk_fma_f32 v[34:35], v[66:67], v[48:49], v[34:35] op_sel_hi:[0,1,1]
	v_mul_f32_e32 v34, 0x41800000, v34
	v_mul_f32_e32 v35, 0x41800000, v35
	v_cvt_pk_fp8_f32 v38, v34, v35 op_sel:[0,0,1]
	global_store_dword v[50:51], v38, off offset:56
	v_mov_b32_e32 v38, v151
	v_lshlrev_b32_e32 v36, 16, v236
	v_and_b32_e32 v37, 0xffff0000, v236
	v_pk_fma_f32 v[18:19], v[66:67], v[18:19], v[36:37] op_sel_hi:[0,1,1]
	v_mul_f32_e32 v18, 0x41800000, v18
	v_mul_f32_e32 v19, 0x41800000, v19
	v_cvt_pk_fp8_f32 v38, v18, v19
	v_lshlrev_b32_e32 v34, 16, v237
	v_and_b32_e32 v35, 0xffff0000, v237
	v_pk_fma_f32 v[18:19], v[66:67], v[20:21], v[34:35] op_sel_hi:[0,1,1]
	v_mul_f32_e32 v18, 0x41800000, v18
	v_mul_f32_e32 v19, 0x41800000, v19
	v_cvt_pk_fp8_f32 v38, v18, v19 op_sel:[0,0,1]
	v_mov_b32_e32 v34, v151
	global_store_dword v[50:51], v38, off offset:64
	v_lshlrev_b32_e32 v20, 16, v238
	v_and_b32_e32 v21, 0xffff0000, v238
	v_pk_fma_f32 v[20:21], v[66:67], v[22:23], v[20:21] op_sel_hi:[0,1,1]
	v_mul_f32_e32 v20, 0x41800000, v20
	v_mul_f32_e32 v21, 0x41800000, v21
	v_cvt_pk_fp8_f32 v34, v20, v21
	v_lshlrev_b32_e32 v18, 16, v239
	v_and_b32_e32 v19, 0xffff0000, v239
	v_pk_fma_f32 v[18:19], v[66:67], v[24:25], v[18:19] op_sel_hi:[0,1,1]
	v_mul_f32_e32 v18, 0x41800000, v18
	v_mul_f32_e32 v19, 0x41800000, v19
	v_cvt_pk_fp8_f32 v34, v18, v19 op_sel:[0,0,1]
	v_mov_b32_e32 v22, v151
	global_store_dword v[50:51], v34, off offset:72
	v_lshlrev_b32_e32 v20, 16, v240
	v_and_b32_e32 v21, 0xffff0000, v240
	v_pk_fma_f32 v[20:21], v[66:67], v[26:27], v[20:21] op_sel_hi:[0,1,1]
	v_mul_f32_e32 v20, 0x41800000, v20
	v_mul_f32_e32 v21, 0x41800000, v21
	v_cvt_pk_fp8_f32 v22, v20, v21
	v_lshlrev_b32_e32 v18, 16, v241
	v_and_b32_e32 v19, 0xffff0000, v241
	v_pk_fma_f32 v[18:19], v[66:67], v[28:29], v[18:19] op_sel_hi:[0,1,1]
	v_mul_f32_e32 v18, 0x41800000, v18
	v_mul_f32_e32 v19, 0x41800000, v19
	v_cvt_pk_fp8_f32 v22, v18, v19 op_sel:[0,0,1]
	global_store_dword v[50:51], v22, off offset:80
	v_mov_b32_e32 v22, v151
	v_lshlrev_b32_e32 v20, 16, v242
	v_and_b32_e32 v21, 0xffff0000, v242
	v_pk_fma_f32 v[20:21], v[66:67], v[30:31], v[20:21] op_sel_hi:[0,1,1]
	v_mul_f32_e32 v20, 0x41800000, v20
	v_mul_f32_e32 v21, 0x41800000, v21
	v_cvt_pk_fp8_f32 v22, v20, v21
	v_lshlrev_b32_e32 v18, 16, v243
	v_and_b32_e32 v19, 0xffff0000, v243
	v_pk_fma_f32 v[18:19], v[66:67], v[32:33], v[18:19] op_sel_hi:[0,1,1]
	v_mul_f32_e32 v18, 0x41800000, v18
	v_mul_f32_e32 v19, 0x41800000, v19
	v_cvt_pk_fp8_f32 v22, v18, v19 op_sel:[0,0,1]
	global_store_dword v[50:51], v22, off offset:88
	v_mov_b32_e32 v22, v151
	v_lshlrev_b32_e32 v20, 16, v246
	v_and_b32_e32 v21, 0xffff0000, v246
	v_pk_fma_f32 v[2:3], v[66:67], v[2:3], v[20:21] op_sel_hi:[0,1,1]
	v_mul_f32_e32 v2, 0x41800000, v2
	v_mul_f32_e32 v3, 0x41800000, v3
	v_cvt_pk_fp8_f32 v22, v2, v3
	v_lshlrev_b32_e32 v18, 16, v247
	v_and_b32_e32 v19, 0xffff0000, v247
	v_pk_fma_f32 v[2:3], v[66:67], v[4:5], v[18:19] op_sel_hi:[0,1,1]
	v_mul_f32_e32 v2, 0x41800000, v2
	v_mul_f32_e32 v3, 0x41800000, v3
	v_cvt_pk_fp8_f32 v22, v2, v3 op_sel:[0,0,1]
	v_mov_b32_e32 v18, v151
	global_store_dword v[50:51], v22, off offset:96
	v_lshlrev_b32_e32 v4, 16, v248
	v_and_b32_e32 v5, 0xffff0000, v248
	v_pk_fma_f32 v[4:5], v[66:67], v[6:7], v[4:5] op_sel_hi:[0,1,1]
	v_mul_f32_e32 v4, 0x41800000, v4
	v_mul_f32_e32 v5, 0x41800000, v5
	v_cvt_pk_fp8_f32 v18, v4, v5
	v_lshlrev_b32_e32 v2, 16, v249
	v_and_b32_e32 v3, 0xffff0000, v249
	v_pk_fma_f32 v[2:3], v[66:67], v[8:9], v[2:3] op_sel_hi:[0,1,1]
	v_mul_f32_e32 v2, 0x41800000, v2
	v_mul_f32_e32 v3, 0x41800000, v3
	v_cvt_pk_fp8_f32 v18, v2, v3 op_sel:[0,0,1]
	v_mov_b32_e32 v6, v151
	global_store_dword v[50:51], v18, off offset:104
	v_lshlrev_b32_e32 v4, 16, v250
	v_and_b32_e32 v5, 0xffff0000, v250
	v_pk_fma_f32 v[4:5], v[66:67], v[10:11], v[4:5] op_sel_hi:[0,1,1]
	v_mul_f32_e32 v4, 0x41800000, v4
	v_mul_f32_e32 v5, 0x41800000, v5
	v_cvt_pk_fp8_f32 v6, v4, v5
	v_lshlrev_b32_e32 v2, 16, v251
	v_and_b32_e32 v3, 0xffff0000, v251
	v_pk_fma_f32 v[2:3], v[66:67], v[12:13], v[2:3] op_sel_hi:[0,1,1]
	v_mul_f32_e32 v2, 0x41800000, v2
	v_mul_f32_e32 v3, 0x41800000, v3
	v_cvt_pk_fp8_f32 v6, v2, v3 op_sel:[0,0,1]
	global_store_dword v[50:51], v6, off offset:112
	v_mov_b32_e32 v6, v151
	v_lshlrev_b32_e32 v4, 16, v252
	v_and_b32_e32 v5, 0xffff0000, v252
	v_pk_fma_f32 v[4:5], v[66:67], v[14:15], v[4:5] op_sel_hi:[0,1,1]
	v_mul_f32_e32 v4, 0x41800000, v4
	v_mul_f32_e32 v5, 0x41800000, v5
	v_cvt_pk_fp8_f32 v6, v4, v5
	v_lshlrev_b32_e32 v2, 16, v253
	v_and_b32_e32 v3, 0xffff0000, v253
	v_pk_fma_f32 v[2:3], v[66:67], v[16:17], v[2:3] op_sel_hi:[0,1,1]
	v_mul_f32_e32 v2, 0x41800000, v2
	v_mul_f32_e32 v3, 0x41800000, v3
	v_cvt_pk_fp8_f32 v6, v2, v3 op_sel:[0,0,1]
	global_store_dword v[50:51], v6, off offset:120
	s_cbranch_vccnz .LBB0_837

; __device__ __forceinline__ u32x2 pack4(f32x4 v) { u32x2 w; w.x = cvtpk(v[0], v[1]); w.y = cvtpk(v[2], v[3]); return w; }
; __device__ __forceinline__ void nsa_unit(Frame& F, int b, int g, int c) {
;     ...
; #pragma unroll
;         for (int db = 0; db < 4; ++db)
; #pragma unroll
;             for (int q4 = 0; q4 < 4; ++q4) { f32x4 o = {O[db][4 * q4], O[db][4 * q4 + 1], O[db][4 * q4 + 2], O[db][4 * q4 + 3]}; *(u32x2*)(accb + 32 * db + 8 * q4 + 4 * hi) = pack4(o * gc); }
;     ...
;         for (int tt = 0; tt < 8; ++tt) {
;             const int tl = 8 * w + tt; unsigned long long mk;
;             if (c >= 16) {
;                 const bool cand = (lane >= 1) && (lane <= c - 2);
;                 const float v = cand ? impG[tl * 64 + lane] + impL[tl * 64 + lane] : -__builtin_inff();
.LBB0_866:
	v_readlane_b32 s0, v244, 1
	v_readlane_b32 s1, v244, 2
	v_lshlrev_b32_e32 v68, 1, v166
	v_mov_b32_e32 v69, v151
	v_lshl_add_u64 v[66:67], v[160:161], 1, s[0:1]
	v_lshl_add_u64 v[66:67], v[66:67], 0, v[68:69]
	v_lshlrev_b32_e32 v68, 3, v159
	v_pk_mul_f32 v[52:53], v[146:147], v[52:53] op_sel_hi:[0,1]
	v_pk_mul_f32 v[50:51], v[146:147], v[50:51] op_sel_hi:[0,1]
	v_pk_mul_f32 v[36:37], v[146:147], v[36:37] op_sel_hi:[0,1]
	v_pk_mul_f32 v[34:35], v[146:147], v[34:35] op_sel_hi:[0,1]
	v_pk_mul_f32 v[20:21], v[146:147], v[20:21] op_sel_hi:[0,1]
	v_pk_mul_f32 v[18:19], v[146:147], v[18:19] op_sel_hi:[0,1]
	v_pk_mul_f32 v[4:5], v[146:147], v[4:5] op_sel_hi:[0,1]
	v_pk_mul_f32 v[2:3], v[146:147], v[2:3] op_sel_hi:[0,1]
	s_cmp_gt_u32 s68, 15
	v_lshl_add_u64 v[160:161], v[66:67], 0, v[68:69]
	v_cvt_pk_bf16_f32 v220, v50, v51
	v_cvt_pk_bf16_f32 v221, v52, v53
	v_cvt_pk_bf16_f32 v228, v34, v35
	v_cvt_pk_bf16_f32 v229, v36, v37
	v_cvt_pk_bf16_f32 v236, v18, v19
	v_cvt_pk_bf16_f32 v237, v20, v21
	v_cvt_pk_bf16_f32 v246, v2, v3
	v_cvt_pk_bf16_f32 v247, v4, v5
	s_cselect_b64 s[6:7], -1, 0
	s_lshl_b64 s[0:1], 2, s68
	v_pk_mul_f32 v[50:51], v[146:147], v[56:57] op_sel_hi:[0,1]
	v_pk_mul_f32 v[52:53], v[146:147], v[54:55] op_sel_hi:[0,1]
	v_pk_mul_f32 v[34:35], v[146:147], v[40:41] op_sel_hi:[0,1]
	v_pk_mul_f32 v[36:37], v[146:147], v[38:39] op_sel_hi:[0,1]
	v_pk_mul_f32 v[18:19], v[146:147], v[24:25] op_sel_hi:[0,1]
	v_pk_mul_f32 v[20:21], v[146:147], v[22:23] op_sel_hi:[0,1]
	v_pk_mul_f32 v[2:3], v[146:147], v[8:9] op_sel_hi:[0,1]
	v_pk_mul_f32 v[4:5], v[146:147], v[6:7] op_sel_hi:[0,1]
	s_add_u32 s26, s0, -1
	v_cvt_pk_bf16_f32 v222, v52, v53
	v_cvt_pk_bf16_f32 v223, v50, v51
	v_cvt_pk_bf16_f32 v230, v36, v37
	v_cvt_pk_bf16_f32 v231, v34, v35
	v_cvt_pk_bf16_f32 v238, v20, v21
	v_cvt_pk_bf16_f32 v239, v18, v19
	v_cvt_pk_bf16_f32 v248, v4, v5
	v_cvt_pk_bf16_f32 v249, v2, v3
	s_addc_u32 s27, s1, -1
	s_add_i32 s0, s68, -2
	v_pk_mul_f32 v[50:51], v[146:147], v[60:61] op_sel_hi:[0,1]
	v_pk_mul_f32 v[52:53], v[146:147], v[58:59] op_sel_hi:[0,1]
	v_pk_mul_f32 v[34:35], v[146:147], v[44:45] op_sel_hi:[0,1]
	v_pk_mul_f32 v[36:37], v[146:147], v[42:43] op_sel_hi:[0,1]
	v_pk_mul_f32 v[18:19], v[146:147], v[28:29] op_sel_hi:[0,1]
	v_pk_mul_f32 v[20:21], v[146:147], v[26:27] op_sel_hi:[0,1]
	v_pk_mul_f32 v[2:3], v[146:147], v[12:13] op_sel_hi:[0,1]
	v_pk_mul_f32 v[4:5], v[146:147], v[10:11] op_sel_hi:[0,1]
	v_cmp_ne_u32_e32 vcc, 0, v163
	v_cmp_ge_i32_e64 s[0:1], s0, v163
	s_add_i32 s2, s68, -1
	v_cvt_pk_bf16_f32 v224, v52, v53
	v_cvt_pk_bf16_f32 v225, v50, v51
	v_cvt_pk_bf16_f32 v232, v36, v37
	v_cvt_pk_bf16_f32 v233, v34, v35
	v_cvt_pk_bf16_f32 v240, v20, v21
	v_cvt_pk_bf16_f32 v241, v18, v19
	v_cvt_pk_bf16_f32 v250, v4, v5
	v_cvt_pk_bf16_f32 v251, v2, v3
	s_and_b64 s[8:9], vcc, s[0:1]
	s_lshl_b64 s[0:1], 1, s68
	s_lshl_b64 s[2:3], 1, s2
	v_pk_mul_f32 v[50:51], v[146:147], v[64:65] op_sel_hi:[0,1]
	v_pk_mul_f32 v[52:53], v[146:147], v[62:63] op_sel_hi:[0,1]
	v_pk_mul_f32 v[34:35], v[146:147], v[48:49] op_sel_hi:[0,1]
	v_pk_mul_f32 v[36:37], v[146:147], v[46:47] op_sel_hi:[0,1]
	v_pk_mul_f32 v[18:19], v[146:147], v[32:33] op_sel_hi:[0,1]
	v_pk_mul_f32 v[20:21], v[146:147], v[30:31] op_sel_hi:[0,1]
	v_pk_mul_f32 v[2:3], v[146:147], v[16:17] op_sel_hi:[0,1]
	v_pk_mul_f32 v[4:5], v[146:147], v[14:15] op_sel_hi:[0,1]
	s_mov_b32 s12, s26
	s_mov_b32 s13, s27
	s_or_b64 s[10:11], s[2:3], s[0:1]
	v_cvt_pk_bf16_f32 v226, v52, v53
	v_cvt_pk_bf16_f32 v227, v50, v51
	v_cvt_pk_bf16_f32 v234, v36, v37
	v_cvt_pk_bf16_f32 v235, v34, v35
	v_cvt_pk_bf16_f32 v242, v20, v21
	v_cvt_pk_bf16_f32 v243, v18, v19
	v_cvt_pk_bf16_f32 v252, v4, v5
	v_cvt_pk_bf16_f32 v253, v2, v3
	s_cmp_lt_u32 s68, 16
	s_mov_b64 s[14:15], s[12:13]
	s_barrier
	s_cbranch_scc1 .LBB0_872
	v_mov_b32_e32 v2, 0xff800000
	s_and_saveexec_b64 s[0:1], s[8:9]
	s_cbranch_execz .LBB0_869
	v_or_b32_e32 v2, s38, v163
	v_lshl_add_u32 v2, v2, 2, 0
	v_add_u32_e32 v3, 0x16800, v2
	v_add_u32_e32 v2, 0x1a800, v2
	ds_read_b32 v3, v3
	ds_read_b32 v2, v2
	s_waitcnt lgkmcnt(0)
	v_add_f32_e32 v2, v3, v2

; __device__ __forceinline__ u32x2 pack4(f32x4 v) { u32x2 w; w.x = cvtpk(v[0], v[1]); w.y = cvtpk(v[2], v[3]); return w; }
; __device__ __forceinline__ void nsa_unit(Frame& F, int b, int g, int c) {
;     ...
;     { const float sc = l > 0.f ? gs / l : 0.f;
; #pragma unroll
;       for (int db = 0; db < 4; ++db)
; #pragma unroll
;           for (int q4 = 0; q4 < 4; ++q4) { bf16_t* p = accb + 32 * db + 8 * q4 + 4 * hi; f32x4 o = {O[db][4 * q4], O[db][4 * q4 + 1], O[db][4 * q4 + 2], O[db][4 * q4 + 3]}; const u32x2 w = *(const u32x2*)p;
;               const f32x4 pr = {__uint_as_float(w.x << 16), __uint_as_float(w.x & 0xffff0000u), __uint_as_float(w.y << 16), __uint_as_float(w.y & 0xffff0000u)}; *(u32x2*)p = pack4(pr + o * sc); } }
;     m = -1e30f; l = 0.f; zero_o(O);
;     run_seq<M_WIN, 8>(lds, tid, qf, O, m, l, C, KV + 4 * 512, 3072, KV, KV + 5 * 512, 3072, c >= 8 ? c - 8 : 0, c, 0ull, ts, ts - 512, 0ull, 0, 0.f, tokl, head);
.LBB0_936:
	v_div_scale_f32 v32, s[0:1], v146, v146, v147
	v_rcp_f32_e32 v34, v32
	v_div_scale_f32 v33, vcc, v147, v146, v147
	v_fma_f32 v35, -v32, v34, 1.0
	v_fmac_f32_e32 v34, v35, v34
	v_mul_f32_e32 v35, v33, v34
	v_fma_f32 v36, -v32, v35, v33
	v_fmac_f32_e32 v35, v36, v34
	v_fma_f32 v32, -v32, v35, v33
	v_div_fmas_f32 v32, v32, v34, v35
	v_div_fixup_f32 v32, v32, v146, v147
	v_cmp_lt_f32_e32 vcc, 0, v146
	s_mov_b32 s0, 0x60000
	v_lshlrev_b64 v[146:147], 1, v[166:167]
	v_cndmask_b32_e32 v32, 0, v32, vcc
	v_lshlrev_b64 v[162:163], 1, v[168:169]
	s_mov_b32 s2, 0
	v_mov_b32_e32 v166, 0
	v_mov_b32_e32 v168, 0xf149f2ca
	v_lshlrev_b32_e32 v34, 16, v220
	v_and_b32_e32 v35, 0xffff0000, v220
	v_lshlrev_b32_e32 v2, 16, v221
	v_and_b32_e32 v3, 0xffff0000, v221
	v_lshlrev_b32_e32 v36, 16, v222
	v_and_b32_e32 v37, 0xffff0000, v222
	v_lshlrev_b32_e32 v4, 16, v223
	v_and_b32_e32 v5, 0xffff0000, v223
	v_lshlrev_b32_e32 v38, 16, v224
	v_and_b32_e32 v39, 0xffff0000, v224
	v_lshlrev_b32_e32 v6, 16, v225
	v_and_b32_e32 v7, 0xffff0000, v225
	v_lshlrev_b32_e32 v40, 16, v226
	v_and_b32_e32 v41, 0xffff0000, v226
	v_lshlrev_b32_e32 v8, 16, v227
	v_and_b32_e32 v9, 0xffff0000, v227
	v_lshlrev_b32_e32 v42, 16, v228
	v_and_b32_e32 v43, 0xffff0000, v228
	v_lshlrev_b32_e32 v10, 16, v229
	v_and_b32_e32 v11, 0xffff0000, v229
	v_lshlrev_b32_e32 v44, 16, v230
	v_and_b32_e32 v45, 0xffff0000, v230
	v_lshlrev_b32_e32 v12, 16, v231
	v_and_b32_e32 v13, 0xffff0000, v231
	v_pk_fma_f32 v[2:3], v[204:205], v[32:33], v[2:3] op_sel_hi:[1,0,1]
	v_pk_fma_f32 v[34:35], v[202:203], v[32:33], v[34:35] op_sel_hi:[1,0,1]
	v_pk_fma_f32 v[4:5], v[200:201], v[32:33], v[4:5] op_sel_hi:[1,0,1]
	v_pk_fma_f32 v[36:37], v[198:199], v[32:33], v[36:37] op_sel_hi:[1,0,1]
	v_pk_fma_f32 v[6:7], v[196:197], v[32:33], v[6:7] op_sel_hi:[1,0,1]
	v_pk_fma_f32 v[38:39], v[194:195], v[32:33], v[38:39] op_sel_hi:[1,0,1]
	v_pk_fma_f32 v[8:9], v[188:189], v[32:33], v[8:9] op_sel_hi:[1,0,1]
	v_pk_fma_f32 v[40:41], v[184:185], v[32:33], v[40:41] op_sel_hi:[1,0,1]
	v_pk_fma_f32 v[10:11], v[192:193], v[32:33], v[10:11] op_sel_hi:[1,0,1]
	v_pk_fma_f32 v[42:43], v[190:191], v[32:33], v[42:43] op_sel_hi:[1,0,1]
	v_pk_fma_f32 v[12:13], v[182:183], v[32:33], v[12:13] op_sel_hi:[1,0,1]
	v_pk_fma_f32 v[44:45], v[180:181], v[32:33], v[44:45] op_sel_hi:[1,0,1]
	v_cvt_pk_bf16_f32 v220, v34, v35
	v_cvt_pk_bf16_f32 v221, v2, v3
	v_cvt_pk_bf16_f32 v222, v36, v37
	v_cvt_pk_bf16_f32 v223, v4, v5
	v_cvt_pk_bf16_f32 v224, v38, v39
	v_cvt_pk_bf16_f32 v225, v6, v7
	v_cvt_pk_bf16_f32 v226, v40, v41
	v_cvt_pk_bf16_f32 v227, v8, v9
	v_cvt_pk_bf16_f32 v228, v42, v43
	v_cvt_pk_bf16_f32 v229, v10, v11
	v_cvt_pk_bf16_f32 v230, v44, v45
	v_cvt_pk_bf16_f32 v231, v12, v13
	v_lshlrev_b32_e32 v2, 16, v232
	v_and_b32_e32 v3, 0xffff0000, v232
	v_lshlrev_b32_e32 v6, 16, v233
	v_and_b32_e32 v7, 0xffff0000, v233
	v_pk_fma_f32 v[6:7], v[178:179], v[32:33], v[6:7] op_sel_hi:[1,0,1]
	v_pk_fma_f32 v[2:3], v[176:177], v[32:33], v[2:3] op_sel_hi:[1,0,1]
	v_sub_u32_e64 v8, s68, 8 clamp
	v_cvt_pk_bf16_f32 v232, v2, v3
	v_cvt_pk_bf16_f32 v233, v6, v7
	v_lshlrev_b32_e32 v2, 16, v234
	v_and_b32_e32 v3, 0xffff0000, v234
	v_lshlrev_b32_e32 v6, 16, v235
	v_and_b32_e32 v7, 0xffff0000, v235
	v_pk_fma_f32 v[6:7], v[174:175], v[32:33], v[6:7] op_sel_hi:[1,0,1]
	v_pk_fma_f32 v[2:3], v[172:173], v[32:33], v[2:3] op_sel_hi:[1,0,1]
	v_mov_b32_e32 v16, v151
	v_cvt_pk_bf16_f32 v234, v2, v3
	v_cvt_pk_bf16_f32 v235, v6, v7
	v_lshlrev_b32_e32 v2, 16, v236
	v_and_b32_e32 v3, 0xffff0000, v236
	v_lshlrev_b32_e32 v6, 16, v237
	v_and_b32_e32 v7, 0xffff0000, v237
	v_pk_fma_f32 v[6:7], v[96:97], v[32:33], v[6:7] op_sel_hi:[1,0,1]
	v_pk_fma_f32 v[2:3], v[94:95], v[32:33], v[2:3] op_sel_hi:[1,0,1]
	v_mov_b32_e32 v17, v151
	v_cvt_pk_bf16_f32 v236, v2, v3
	v_cvt_pk_bf16_f32 v237, v6, v7
	v_lshlrev_b32_e32 v2, 16, v238
	v_and_b32_e32 v3, 0xffff0000, v238
	v_lshlrev_b32_e32 v6, 16, v239
	v_and_b32_e32 v7, 0xffff0000, v239
	v_pk_fma_f32 v[6:7], v[92:93], v[32:33], v[6:7] op_sel_hi:[1,0,1]
	v_pk_fma_f32 v[2:3], v[90:91], v[32:33], v[2:3] op_sel_hi:[1,0,1]
	v_readfirstlane_b32 s3, v8
	v_cvt_pk_bf16_f32 v238, v2, v3
	v_cvt_pk_bf16_f32 v239, v6, v7
	v_lshlrev_b32_e32 v2, 16, v240
	v_and_b32_e32 v3, 0xffff0000, v240
	v_lshlrev_b32_e32 v6, 16, v241
	v_and_b32_e32 v7, 0xffff0000, v241
	v_pk_fma_f32 v[6:7], v[88:89], v[32:33], v[6:7] op_sel_hi:[1,0,1]
	v_pk_fma_f32 v[2:3], v[86:87], v[32:33], v[2:3] op_sel_hi:[1,0,1]
	v_mov_b32_e32 v9, v151
	v_cvt_pk_bf16_f32 v240, v2, v3
	v_cvt_pk_bf16_f32 v241, v6, v7
	v_lshlrev_b32_e32 v2, 16, v242
	v_and_b32_e32 v3, 0xffff0000, v242
	v_lshlrev_b32_e32 v6, 16, v243
	v_and_b32_e32 v7, 0xffff0000, v243
	v_pk_fma_f32 v[6:7], v[84:85], v[32:33], v[6:7] op_sel_hi:[1,0,1]
	v_pk_fma_f32 v[2:3], v[82:83], v[32:33], v[2:3] op_sel_hi:[1,0,1]
	v_mov_b32_e32 v10, v151
	v_cvt_pk_bf16_f32 v242, v2, v3
	v_cvt_pk_bf16_f32 v243, v6, v7
	v_lshlrev_b32_e32 v2, 16, v246
	v_and_b32_e32 v3, 0xffff0000, v246
	v_lshlrev_b32_e32 v6, 16, v247
	v_and_b32_e32 v7, 0xffff0000, v247
	v_pk_fma_f32 v[6:7], v[80:81], v[32:33], v[6:7] op_sel_hi:[1,0,1]
	v_pk_fma_f32 v[2:3], v[78:79], v[32:33], v[2:3] op_sel_hi:[1,0,1]
	v_mov_b32_e32 v11, v151
	v_cvt_pk_bf16_f32 v246, v2, v3
	v_cvt_pk_bf16_f32 v247, v6, v7
	v_lshlrev_b32_e32 v2, 16, v248
	v_and_b32_e32 v3, 0xffff0000, v248
	v_lshlrev_b32_e32 v6, 16, v249
	v_and_b32_e32 v7, 0xffff0000, v249
	v_pk_fma_f32 v[6:7], v[76:77], v[32:33], v[6:7] op_sel_hi:[1,0,1]
	v_pk_fma_f32 v[2:3], v[74:75], v[32:33], v[2:3] op_sel_hi:[1,0,1]
	v_mov_b32_e32 v12, v151
	v_cvt_pk_bf16_f32 v248, v2, v3
	v_cvt_pk_bf16_f32 v249, v6, v7
	v_lshlrev_b32_e32 v2, 16, v250
	v_and_b32_e32 v3, 0xffff0000, v250
	v_lshlrev_b32_e32 v6, 16, v251
	v_and_b32_e32 v7, 0xffff0000, v251
	v_pk_fma_f32 v[6:7], v[72:73], v[32:33], v[6:7] op_sel_hi:[1,0,1]
	v_pk_fma_f32 v[2:3], v[70:71], v[32:33], v[2:3] op_sel_hi:[1,0,1]
	v_mov_b32_e32 v13, v151
	v_cvt_pk_bf16_f32 v250, v2, v3
	v_cvt_pk_bf16_f32 v251, v6, v7
	v_lshlrev_b32_e32 v2, 16, v252
	v_and_b32_e32 v3, 0xffff0000, v252
	v_lshlrev_b32_e32 v4, 16, v253
	v_and_b32_e32 v5, 0xffff0000, v253
	v_pk_fma_f32 v[4:5], v[68:69], v[32:33], v[4:5] op_sel_hi:[1,0,1]
	v_pk_fma_f32 v[2:3], v[66:67], v[32:33], v[2:3] op_sel_hi:[1,0,1]
	v_mov_b32_e32 v14, v151
	v_cvt_pk_bf16_f32 v252, v2, v3
	v_cvt_pk_bf16_f32 v253, v4, v5
	v_mul_lo_u32 v2, v8, s0
	v_mov_b32_e32 v3, v151
	v_lshl_add_u64 v[4:5], s[90:91], 0, v[2:3]
	v_lshl_add_u64 v[6:7], v[4:5], 0, v[146:147]
	v_lshl_add_u64 v[4:5], v[4:5], 0, v[162:163]
	v_lshl_add_u64 v[2:3], s[92:93], 0, v[2:3]
	v_lshl_add_u64 v[6:7], v[6:7], 0, v[150:151]
	v_lshl_add_u64 v[4:5], v[4:5], 0, v[150:151]
	s_barrier
; template <int MODE, int NQ> ...
;     ...
;     int j; unsigned long long rem = 0ull;
;     if (MODE == M_SEL) { rem = tmask; j = rem ? (int)__builtin_ctzll(rem) : -1; rem &= rem - 1ull; } else { j = jlo <= jhi ? jlo : -1; }
;     Stage st;
;     __syncthreads();
;     if (j >= 0) stage_load<HASP, HASV>(st, Kg + (size_t)j * 64 * ldk, ldk, Pg + (size_t)j * 64 * 64, Vg + (size_t)j * 64 * ldv, ldv, tid);
; __device__ __forceinline__ void nsa_unit(Frame& F, int b, int g, int c) {
;     ...
;     m = -1e30f; l = 0.f; zero_o(O);
;     run_seq<M_WIN, 8>(lds, tid, qf, O, m, l, C, KV + 4 * 512, 3072, KV, KV + 5 * 512, 3072, c >= 8 ? c - 8 : 0, c, 0ull, ts, ts - 512, 0ull, 0, 0.f, tokl, head);
	global_load_dwordx4 v[130:133], v[6:7], off
	global_load_dwordx4 v[134:137], v[4:5], off
	v_lshl_add_u64 v[4:5], v[2:3], 0, v[146:147]
	v_lshl_add_u64 v[4:5], v[4:5], 0, v[150:151]
	v_lshl_add_u64 v[2:3], v[2:3], 0, v[162:163]
	v_lshl_add_u64 v[2:3], v[2:3], 0, v[150:151]
	global_load_dwordx4 v[138:141], v[4:5], off
	global_load_dwordx4 v[142:145], v[2:3], off
	s_min_u32 s0, s68, 8
	s_lshl_b32 s0, s0, 6
	s_add_i32 s0, s0, s74
	v_add_u32_e32 v2, s0, v210
	v_sub_u32_e32 v164, v2, v158
	v_mov_b32_e32 v2, v151
	v_mov_b32_e32 v3, v151
	v_mov_b32_e32 v4, v151
	v_mov_b32_e32 v5, v151
	v_mov_b32_e32 v6, v151
	v_mov_b32_e32 v7, v151
	v_mov_b32_e32 v8, v151
	v_mov_b32_e32 v15, v151
	v_mov_b64_e32 v[32:33], v[16:17]
	v_mov_b64_e32 v[48:49], v[16:17]
	v_mov_b64_e32 v[64:65], v[16:17]
	v_mov_b64_e32 v[30:31], v[14:15]
	v_mov_b64_e32 v[28:29], v[12:13]
	v_mov_b64_e32 v[26:27], v[10:11]
	v_mov_b64_e32 v[24:25], v[8:9]
	v_mov_b64_e32 v[22:23], v[6:7]
	v_mov_b64_e32 v[20:21], v[4:5]
	v_mov_b64_e32 v[18:19], v[2:3]
	v_mov_b64_e32 v[46:47], v[14:15]
	v_mov_b64_e32 v[44:45], v[12:13]
	v_mov_b64_e32 v[42:43], v[10:11]
	v_mov_b64_e32 v[40:41], v[8:9]
	v_mov_b64_e32 v[38:39], v[6:7]
	v_mov_b64_e32 v[36:37], v[4:5]
	v_mov_b64_e32 v[34:35], v[2:3]
	v_mov_b64_e32 v[62:63], v[14:15]
	v_mov_b64_e32 v[60:61], v[12:13]
	v_mov_b64_e32 v[58:59], v[10:11]
	v_mov_b64_e32 v[56:57], v[8:9]
	v_mov_b64_e32 v[54:55], v[6:7]
	v_mov_b64_e32 v[52:53], v[4:5]
	v_mov_b64_e32 v[50:51], v[2:3]
